# idx top-k bisection: second and third probes at fixed thresholds 0.125 and 2.0
# speedup vs baseline: 1.0120x; 1.0120x over previous
.Lsel_search:
	s_mov_b32 s29, 0x00800000
	s_mov_b32 s30, 0xff800000
	s_mov_b32 s31, -1
	s_mov_b32 s45, 0
.Lsel_bis:
	s_sub_u32 s0, s30, s29
	s_cmp_lt_u32 s0, 2
	s_cbranch_scc1 .Lsel_bis_done
	s_lshr_b32 s0, s0, 1
	s_add_u32 s6, s29, s0
	s_add_u32 s45, s45, 1
	s_cmp_gt_u32 s45, 3
	s_cbranch_scc1 .Lsel_nocand
	s_cmp_lt_u32 s45, 2
	s_cbranch_scc1 .Lsel_nocand
	s_mov_b32 s0, 0xc0000000
	s_cmp_eq_u32 s45, 2
	s_cselect_b32 s0, 0xbe000000, s0
	s_cmp_gt_u32 s0, s29
	s_cselect_b32 s1, s0, s6
	s_cmp_lt_u32 s0, s30
	s_cselect_b32 s6, s1, s6
.Lsel_nocand:
	s_mov_b32 s7, s6
	s_sub_u32 s1, s7, 0x60800000
	s_cmp_lt_u32 s1, 0x3f000000
	s_cbranch_scc0 .Lsel_nosnap1
	s_mov_b32 s1, 0x9f800000
	s_cmp_lt_u32 s7, 0x80000000
	s_cselect_b32 s1, 0x80000000, s1
	s_cmp_eq_u32 s7, 0x80000000
	s_cselect_b32 s7, s7, s1
